# v034
# baseline (speedup 1.0000x reference)
; #define ISSUE_K(t, slot) do { const char* kg_ = (const char*)(Kh + (long)(t) * (KVBLK * 192)); char* kl_ = K_lds + (slot) * SHM_K + tid * 16; \
;     DMA16(kg_ + kso0, kl_); DMA16(kg_ + kso1, kl_ + 8192); DMA16(kg_ + kso2, kl_ + 16384); } while (0)
; #define ISSUE_V(t, slot) do { const char* vg_ = (const char*)(Vh + (long)(t) * (KVBLK * 128)); char* vl_ = V_lds + (slot) * SHM_V + tid * 16; \
;     DMA16(vg_ + vso0, vl_); DMA16(vg_ + vso1, vl_ + 8192); } while (0)
; #define TBAR(n) do { asm volatile("s_waitcnt vmcnt(" #n ") lgkmcnt(0)" ::: "memory"); __builtin_amdgcn_s_barrier(); SBAR(); } while (0)
; __device__ __forceinline__ void qkt(f32x16& p0, f32x16& p1, const char* Ks, const bf16x8* qr, int r32, int hi) {
;   p0 = f32x16{}; p1 = f32x16{};
; #pragma unroll
;   for (int d0 = 0; d0 < 12; ++d0) { int cb = (d0 * 16 + hi * 8) * 2;
;     bf16x8 b0 = *reinterpret_cast<const bf16x8*>(Ks + KSWZ(r32, cb));
;     bf16x8 b1 = *reinterpret_cast<const bf16x8*>(Ks + KSWZ(32 + r32, cb));
;     p0 = __builtin_amdgcn_mfma_f32_32x32x16_bf16(b0, qr[d0], p0, 0, 0, 0);
;     p1 = __builtin_amdgcn_mfma_f32_32x32x16_bf16(b1, qr[d0], p1, 0, 0, 0); }
; }
; __device__ __forceinline__ void attn_body(const u16* __restrict__ Qb, const u16* __restrict__ Kh, const u16* __restrict__ Vh,
;                                           u16* __restrict__ Ob, int seq, int wvs) {
;     ...
;     TBAR(5);
;     ISSUE_K(j + 2, NEXT3(NEXT3(sK))); ISSUE_V(j + 1, NEXT3(NEXT3(sV)));
;     qkt(pB0, pB1, K_lds + sK * SHM_K, qr, r32, hi);
.LBB0_331:
	s_waitcnt vmcnt(5) lgkmcnt(0)
	s_barrier
	s_add_i32 s4, s31, 1
	s_cmp_lg_u32 s31, 2
	s_cselect_b32 s13, s4, 0
	s_mul_i32 s15, s13, 0x6000
	s_add_i32 s10, s15, 0x6000
	s_cmp_eq_u32 s13, 2
	s_cselect_b64 s[4:5], -1, 0
	s_and_b64 s[8:9], s[4:5], exec
	s_cselect_b32 s8, 0, s10
	s_lshl_b32 vcc_lo, s69, 4
	s_add_i32 vcc_lo, vcc_lo, s8
	s_add_i32 vcc_hi, vcc_lo, 0xc000
	s_mov_b32 m0, vcc_hi
	s_add_i32 vcc_hi, vcc_lo, 0xe000
	global_load_lds_dwordx4 v166, s[98:99]
	s_mov_b32 m0, vcc_hi
	s_add_i32 vcc_hi, vcc_lo, 0x10000
	global_load_lds_dwordx4 v167, s[98:99]
	s_mov_b32 m0, vcc_hi
	s_add_i32 s8, s12, 1
	s_cmp_lg_u32 s12, 2
	s_cselect_b32 s16, s8, 0
	s_lshl_b32 s14, s16, 14
	s_add_i32 s17, s14, 0x4000
	s_cmp_eq_u32 s16, 2
	s_cselect_b64 s[8:9], -1, 0
	s_and_b64 s[10:11], s[8:9], exec
	s_cselect_b32 s10, 0, s17
	global_load_lds_dwordx4 v168, s[98:99]
	s_lshl_b32 vcc_lo, s69, 4
	s_add_i32 vcc_lo, vcc_lo, s10
	s_mov_b32 m0, vcc_lo
	s_add_i32 vcc_hi, vcc_lo, 0x2000
	global_load_lds_dwordx4 v169, s[100:101]
	s_mov_b32 m0, vcc_hi
	s_add_u32 s98, s98, 0x6000
	s_addc_u32 s99, s99, 0
	global_load_lds_dwordx4 v170, s[100:101]
	s_add_u32 s100, s100, 0x4000
	s_addc_u32 s101, s101, 0
	s_mul_i32 s10, s31, 0x6000
	s_add_i32 s10, s10, 0
	v_add_u32_e32 v162, s10, v193
	v_add_u32_e32 v253, s10, v199
	v_add_u32_e32 v252, s10, v200
	v_add_u32_e32 v244, s10, v202
	ds_read_b128 v[64:67], v162 offset:49152
	ds_read_b128 v[68:71], v162 offset:61440
	ds_read_b128 v[228:231], v253 offset:49152
	ds_read_b128 v[232:235], v253 offset:61440
	s_waitcnt lgkmcnt(2)
	v_mfma_f32_32x32x16_bf16 v[80:95], v[64:67], v[140:143], 0
	ds_read_b128 v[236:239], v252 offset:49152
	ds_read_b128 v[240:243], v252 offset:61440
	v_exp_f32_e32 v158, v158
	v_exp_f32_e32 v159, v159
	v_exp_f32_e32 v156, v156
	v_exp_f32_e32 v157, v157
	v_mfma_f32_32x32x16_bf16 v[64:79], v[68:71], v[140:143], 0
	v_exp_f32_e32 v154, v154
	v_exp_f32_e32 v155, v155
	v_exp_f32_e32 v163, v153
	v_exp_f32_e32 v206, v150
	v_exp_f32_e32 v227, v151
	v_cvt_pk_bf16_f32 v150, v214, v216
	v_cvt_pk_bf16_f32 v151, v217, v219
	s_waitcnt lgkmcnt(2)
	v_mfma_f32_32x32x16_bf16 v[64:79], v[232:235], v[136:139], v[64:79]
	v_cvt_pk_bf16_f32 v153, v156, v157
	v_mfma_f32_32x32x16_bf16 v[80:95], v[228:231], v[136:139], v[80:95]
	ds_read_b128 v[228:231], v244 offset:49152
	ds_read_b128 v[232:235], v244 offset:61440
	s_waitcnt lgkmcnt(2)
	v_mfma_f32_32x32x16_bf16 v[64:79], v[240:243], v[132:135], v[64:79]
	v_mfma_f32_32x32x16_bf16 v[80:95], v[236:239], v[132:135], v[80:95]
	ds_read_b128 v[236:239], v162 offset:49280
	ds_read_b128 v[240:243], v162 offset:61568
	s_waitcnt lgkmcnt(2)
	v_mfma_f32_32x32x16_bf16 v[64:79], v[232:235], v[128:131], v[64:79]
	v_mfma_f32_32x32x16_bf16 v[80:95], v[228:231], v[128:131], v[80:95]
	ds_read_b128 v[228:231], v253 offset:49280
	ds_read_b128 v[232:235], v253 offset:61568
	s_waitcnt lgkmcnt(2)
	v_mfma_f32_32x32x16_bf16 v[64:79], v[240:243], v[124:127], v[64:79]
	v_mfma_f32_32x32x16_bf16 v[80:95], v[236:239], v[124:127], v[80:95]
	ds_read_b128 v[236:239], v252 offset:49280
	ds_read_b128 v[240:243], v252 offset:61568
	s_waitcnt lgkmcnt(2)
	v_mfma_f32_32x32x16_bf16 v[64:79], v[232:235], v[120:123], v[64:79]
	v_mfma_f32_32x32x16_bf16 v[80:95], v[228:231], v[120:123], v[80:95]
	ds_read_b128 v[228:231], v244 offset:49280
	ds_read_b128 v[232:235], v244 offset:61568
	s_waitcnt lgkmcnt(2)
	v_mfma_f32_32x32x16_bf16 v[64:79], v[240:243], v[116:119], v[64:79]
	v_mfma_f32_32x32x16_bf16 v[80:95], v[236:239], v[116:119], v[80:95]
	ds_read_b128 v[236:239], v162 offset:49408
	ds_read_b128 v[240:243], v162 offset:61696
	s_waitcnt lgkmcnt(2)
	v_mfma_f32_32x32x16_bf16 v[64:79], v[232:235], v[112:115], v[64:79]
	v_mfma_f32_32x32x16_bf16 v[80:95], v[228:231], v[112:115], v[80:95]
	ds_read_b128 v[228:231], v253 offset:49408
	ds_read_b128 v[232:235], v253 offset:61696
	s_waitcnt lgkmcnt(2)
	v_mfma_f32_32x32x16_bf16 v[64:79], v[240:243], v[108:111], v[64:79]
	v_mfma_f32_32x32x16_bf16 v[80:95], v[236:239], v[108:111], v[80:95]
	ds_read_b128 v[236:239], v252 offset:49408
	ds_read_b128 v[240:243], v252 offset:61696
	s_waitcnt lgkmcnt(2)
	v_mfma_f32_32x32x16_bf16 v[64:79], v[232:235], v[104:107], v[64:79]
	v_mfma_f32_32x32x16_bf16 v[80:95], v[228:231], v[104:107], v[80:95]
	ds_read_b128 v[228:231], v244 offset:49408
	ds_read_b128 v[232:235], v244 offset:61696
	v_lshl_add_u32 v252, s12, 14, v190
	ds_read_b64_tr_b16 v[244:245], v252
	ds_read_b64_tr_b16 v[246:247], v252 offset:2048
	ds_read_b64_tr_b16 v[248:249], v252 offset:4096
	ds_read_b64_tr_b16 v[250:251], v252 offset:6144
	v_exp_f32_e32 v162, v152
	v_cvt_pk_bf16_f32 v152, v158, v159
	s_waitcnt lgkmcnt(6)
	v_mfma_f32_32x32x16_bf16 v[64:79], v[240:243], v[100:103], v[64:79]
	v_mfma_f32_32x32x16_bf16 v[80:95], v[236:239], v[100:103], v[80:95]
	s_waitcnt lgkmcnt(4)
; __device__ __forceinline__ void partialSM(f32x16& p0, f32x16& p1, float& m_reg, float& mn, float& alpha) {
;   constexpr float C = ASCALE * 1.4426950408889634f;
;   float pmax = p0[0]; for (int r = 1; r < 16; ++r) pmax = fmaxf(pmax, p0[r]); for (int r = 0; r < 16; ++r) pmax = fmaxf(pmax, p1[r]);
;   { auto rr = __builtin_amdgcn_permlane32_swap(__float_as_uint(pmax), __float_as_uint(pmax), false, false);
;     pmax = fmaxf(__uint_as_float(rr[0]), __uint_as_float(rr[1])); }
;   if (__builtin_expect(__all(pmax - m_reg <= THR / ASCALE), 1)) { mn = m_reg; alpha = 1.f; }
;   else { mn = fmaxf(m_reg, pmax); alpha = __builtin_amdgcn_exp2f((m_reg - mn) * C); m_reg = mn; }
;   float mnC = -mn * C;
;   for (int r = 0; r < 16; ++r) p0[r] = fmaf(p0[r], C, mnC); for (int r = 0; r < 16; ++r) p1[r] = fmaf(p1[r], C, mnC);
;   for (int r = 0; r < 16; ++r) p0[r] = __builtin_amdgcn_exp2f(p0[r]);
; }
; __device__ __forceinline__ void finishSM(f32x16& p0, f32x16& p1, float alpha, float& l_reg, bf16x8& pa0, bf16x8& pa1, bf16x8& pa2, bf16x8& pa3) {
;   for (int r = 0; r < 16; ++r) p1[r] = __builtin_amdgcn_exp2f(p1[r]);
;   float ps = 0; for (int r = 0; r < 16; ++r) ps += p0[r]; for (int r = 0; r < 16; ++r) ps += p1[r];
;   { auto rr = __builtin_amdgcn_permlane32_swap(__float_as_uint(ps), __float_as_uint(ps), false, false);
;     ps = __uint_as_float(rr[0]) + __uint_as_float(rr[1]); }
;   l_reg = l_reg * alpha + ps;
;     ...
;   PK4(p0, 0, pa0); PK4(p0, 8, pa1); PK4(p1, 0, pa2); PK4(p1, 8, pa3);
;     ...
; }
; __device__ __forceinline__ void qkt(f32x16& p0, f32x16& p1, const char* Ks, const bf16x8* qr, int r32, int hi) {
;   p0 = f32x16{}; p1 = f32x16{};
; #pragma unroll
;   for (int d0 = 0; d0 < 12; ++d0) { int cb = (d0 * 16 + hi * 8) * 2;
;     bf16x8 b0 = *reinterpret_cast<const bf16x8*>(Ks + KSWZ(r32, cb));
;     bf16x8 b1 = *reinterpret_cast<const bf16x8*>(Ks + KSWZ(32 + r32, cb));
;     p0 = __builtin_amdgcn_mfma_f32_32x32x16_bf16(b0, qr[d0], p0, 0, 0, 0);
;     p1 = __builtin_amdgcn_mfma_f32_32x32x16_bf16(b1, qr[d0], p1, 0, 0, 0); }
; }
; __device__ __forceinline__ int v_st(int k, int c) { const int kk = (k & ~0xC) | ((k & 4) << 1) | ((k & 8) >> 1); return ((kk >> 3) * 4 + (c >> 5)) * 512 + ((kk & 7) * 32 + (c & 31)) * 2; }
; __device__ __forceinline__ int v_rd_base(int lane) { return ((lane & 3) << 3) | (((lane >> 2) & 3) << 6) | (((lane >> 4) & 1) << 5) | (((lane >> 5) & 1) << 8); }
	v_mfma_f32_32x32x16_bf16 v[64:79], v[232:235], v[96:99], v[64:79]
	v_exp_f32_e32 v232, v144
	v_add_f32_e32 v144, v218, v220
	v_add_f32_e32 v144, v221, v144
	v_add_f32_e32 v144, v222, v144
	v_add_f32_e32 v144, v223, v144
	v_add_f32_e32 v144, v225, v144
	v_add_f32_e32 v144, v224, v144
	v_add_f32_e32 v144, v226, v144
	v_add_f32_e32 v144, v211, v144
	v_add_f32_e32 v144, v212, v144
	v_add_f32_e32 v144, v213, v144
	v_add_f32_e32 v144, v215, v144
	v_add_f32_e32 v144, v214, v144
	v_add_f32_e32 v144, v216, v144
	v_add_f32_e32 v144, v217, v144
	v_add_f32_e32 v144, v219, v144
	v_add_f32_e32 v144, v158, v144
	v_add_f32_e32 v144, v159, v144
	v_add_f32_e32 v144, v156, v144
	v_add_f32_e32 v144, v157, v144
	v_add_f32_e32 v144, v154, v144
	v_add_f32_e32 v144, v155, v144
	v_mfma_f32_32x32x16_bf16 v[80:95], v[228:231], v[96:99], v[80:95]
	v_exp_f32_e32 v228, v148
	v_add_f32_e32 v144, v162, v144
	v_exp_f32_e32 v229, v149
	v_add_f32_e32 v144, v163, v144
	v_exp_f32_e32 v230, v146
	v_add_f32_e32 v144, v206, v144
	v_exp_f32_e32 v231, v147
	v_add_f32_e32 v144, v227, v144
	v_add_f32_e32 v144, v228, v144
	v_exp_f32_e32 v233, v145
	v_add_f32_e32 v144, v229, v144
	v_add_f32_e32 v144, v230, v144
	v_add_f32_e32 v144, v231, v144
	v_add_f32_e32 v144, v232, v144
	v_add_f32_e32 v209, v233, v144
	v_cvt_pk_bf16_f32 v144, v218, v220
	v_cvt_pk_bf16_f32 v145, v221, v222
	v_cvt_pk_bf16_f32 v146, v223, v225
	v_cvt_pk_bf16_f32 v147, v224, v226
	v_cvt_pk_bf16_f32 v154, v154, v155
	v_cvt_pk_bf16_f32 v155, v162, v163
	v_cvt_pk_bf16_f32 v148, v211, v212
	v_cvt_pk_bf16_f32 v149, v213, v215
	v_cvt_pk_bf16_f32 v156, v206, v227
	ds_read_b64_tr_b16 v[220:221], v252 offset:8192
	ds_read_b64_tr_b16 v[222:223], v252 offset:10240
	ds_read_b64_tr_b16 v[224:225], v252 offset:12288
	ds_read_b64_tr_b16 v[226:227], v252 offset:14336
	s_waitcnt lgkmcnt(4)
	v_mfma_f32_32x32x16_bf16 v[0:15], v[144:147], v[244:247], v[0:15]
	ds_read_b64_tr_b16 v[212:213], v252 offset:512
	ds_read_b64_tr_b16 v[214:215], v252 offset:2560
	v_mfma_f32_32x32x16_bf16 v[0:15], v[148:151], v[248:251], v[0:15]
	ds_read_b64_tr_b16 v[216:217], v252 offset:4608
	ds_read_b64_tr_b16 v[218:219], v252 offset:6656
	v_cvt_pk_bf16_f32 v157, v228, v229
	v_cvt_pk_bf16_f32 v158, v230, v231
	v_cvt_pk_bf16_f32 v159, v232, v233
	s_waitcnt lgkmcnt(6)
	v_mfma_f32_32x32x16_bf16 v[0:15], v[152:155], v[220:223], v[0:15]
	ds_read_b64_tr_b16 v[220:221], v252 offset:8704
	ds_read_b64_tr_b16 v[222:223], v252 offset:10752
	v_mov_b32_e32 v210, v209
	s_nop 1
	v_permlane32_swap_b32_e32 v209, v210
	v_mov_b32_e32 v211, 1.0
	s_waitcnt lgkmcnt(6)
	v_mfma_f32_32x32x16_bf16 v[0:15], v[156:159], v[224:227], v[0:15]
	ds_read_b64_tr_b16 v[224:225], v252 offset:12800
	ds_read_b64_tr_b16 v[226:227], v252 offset:14848
	s_waitcnt lgkmcnt(6)
	v_mfma_f32_32x32x16_bf16 v[48:63], v[144:147], v[212:215], v[48:63]
	ds_read_b64_tr_b16 v[212:213], v252 offset:1024
	ds_read_b64_tr_b16 v[214:215], v252 offset:3072
	s_waitcnt lgkmcnt(6)
	v_mfma_f32_32x32x16_bf16 v[48:63], v[148:151], v[216:219], v[48:63]
	ds_read_b64_tr_b16 v[216:217], v252 offset:5120
	ds_read_b64_tr_b16 v[218:219], v252 offset:7168
	s_waitcnt lgkmcnt(6)
	v_mfma_f32_32x32x16_bf16 v[48:63], v[152:155], v[220:223], v[48:63]
	ds_read_b64_tr_b16 v[220:221], v252 offset:9216
	ds_read_b64_tr_b16 v[222:223], v252 offset:11264
	s_waitcnt lgkmcnt(6)
	v_mfma_f32_32x32x16_bf16 v[48:63], v[156:159], v[224:227], v[48:63]
	ds_read_b64_tr_b16 v[224:225], v252 offset:13312
	ds_read_b64_tr_b16 v[226:227], v252 offset:15360
	s_waitcnt lgkmcnt(6)
	v_mfma_f32_32x32x16_bf16 v[32:47], v[144:147], v[212:215], v[32:47]
	ds_read_b64_tr_b16 v[212:213], v252 offset:1536
	ds_read_b64_tr_b16 v[214:215], v252 offset:3584
	s_waitcnt lgkmcnt(6)
	v_mfma_f32_32x32x16_bf16 v[32:47], v[148:151], v[216:219], v[32:47]
	ds_read_b64_tr_b16 v[216:217], v252 offset:5632
	ds_read_b64_tr_b16 v[218:219], v252 offset:7680
	s_waitcnt lgkmcnt(6)
	v_mfma_f32_32x32x16_bf16 v[32:47], v[152:155], v[220:223], v[32:47]
	ds_read_b64_tr_b16 v[220:221], v252 offset:9728
	ds_read_b64_tr_b16 v[222:223], v252 offset:11776
	s_waitcnt lgkmcnt(6)
	v_mfma_f32_32x32x16_bf16 v[32:47], v[156:159], v[224:227], v[32:47]
	ds_read_b64_tr_b16 v[224:225], v252 offset:13824
	ds_read_b64_tr_b16 v[226:227], v252 offset:15872
	s_waitcnt lgkmcnt(6)
	v_mfma_f32_32x32x16_bf16 v[16:31], v[144:147], v[212:215], v[16:31]
	v_max_f32_e32 v144, v80, v81
	v_max3_f32 v144, v144, v82, v83
	v_max3_f32 v144, v144, v84, v85
	v_max3_f32 v144, v144, v86, v87
	v_max3_f32 v144, v144, v88, v89
	s_waitcnt lgkmcnt(4)
	v_mfma_f32_32x32x16_bf16 v[16:31], v[148:151], v[216:219], v[16:31]
	v_max3_f32 v144, v144, v90, v91
	v_max3_f32 v144, v144, v92, v93
	v_max3_f32 v144, v144, v94, v95
	v_max3_f32 v144, v144, v64, v65
	v_max3_f32 v144, v144, v66, v67
	v_max3_f32 v144, v144, v68, v69
	v_max3_f32 v144, v144, v70, v71
	s_waitcnt lgkmcnt(2)
	v_mfma_f32_32x32x16_bf16 v[16:31], v[152:155], v[220:223], v[16:31]
	v_max3_f32 v144, v144, v72, v73
	v_max3_f32 v144, v144, v74, v75
	v_max3_f32 v144, v144, v76, v77
	v_max3_f32 v144, v144, v78, v79
	v_mov_b32_e32 v145, v144
	s_nop 1
	v_permlane32_swap_b32_e32 v144, v145
	s_waitcnt lgkmcnt(0)
	v_mfma_f32_32x32x16_bf16 v[16:31], v[156:159], v[224:227], v[16:31]
	v_max_f32_e32 v144, v144, v145
	v_sub_f32_e32 v145, v144, v191
	v_cmp_ge_f32_e32 vcc, s35, v145
	s_cmp_eq_u64 vcc, exec
	s_cbranch_scc0 .LBB0_344
	v_cmp_gt_f32_e32 vcc, 1.0, v211
	s_cbranch_vccz .LBB0_336

; #define ISSUE_K(t, slot) do { const char* kg_ = (const char*)(Kh + (long)(t) * (KVBLK * 192)); char* kl_ = K_lds + (slot) * SHM_K + tid * 16; \
;     DMA16(kg_ + kso0, kl_); DMA16(kg_ + kso1, kl_ + 8192); DMA16(kg_ + kso2, kl_ + 16384); } while (0)
; #define ISSUE_V(t, slot) do { const char* vg_ = (const char*)(Vh + (long)(t) * (KVBLK * 128)); char* vl_ = V_lds + (slot) * SHM_V + tid * 16; \
;     DMA16(vg_ + vso0, vl_); DMA16(vg_ + vso1, vl_ + 8192); } while (0)
; #define TBAR(n) do { asm volatile("s_waitcnt vmcnt(" #n ") lgkmcnt(0)" ::: "memory"); __builtin_amdgcn_s_barrier(); SBAR(); } while (0)
; __device__ __forceinline__ void partialSM(f32x16& p0, f32x16& p1, float& m_reg, float& mn, float& alpha) {
;     ...
;   else { mn = fmaxf(m_reg, pmax); alpha = __builtin_amdgcn_exp2f((m_reg - mn) * C); m_reg = mn; }
;   float mnC = -mn * C;
;   for (int r = 0; r < 16; ++r) p0[r] = fmaf(p0[r], C, mnC); for (int r = 0; r < 16; ++r) p1[r] = fmaf(p1[r], C, mnC);
;   for (int r = 0; r < 16; ++r) p0[r] = __builtin_amdgcn_exp2f(p0[r]);
; }
; __device__ __forceinline__ void finishSM(f32x16& p0, f32x16& p1, float alpha, float& l_reg, bf16x8& pa0, bf16x8& pa1, bf16x8& pa2, bf16x8& pa3) {
;   for (int r = 0; r < 16; ++r) p1[r] = __builtin_amdgcn_exp2f(p1[r]);
; __device__ __forceinline__ void attn_body(const u16* __restrict__ Qb, const u16* __restrict__ Kh, const u16* __restrict__ Vh,
;                                           u16* __restrict__ Ob, int seq, int wvs) {
;     ...
;     TBAR(5);
;     if (j + 3 < NT) ISSUE_K(j + 3, NEXT3(NEXT3(sK)));
;     ISSUE_V(j + 2, NEXT3(NEXT3(sV)));
;     qkt(pA0, pA1, K_lds + sK * SHM_K, qr, r32, hi);
.LBB0_338:
	s_add_u32 s98, s98, 0x6000
	s_addc_u32 s99, s99, 0
	s_add_i32 s16, s16, 1
	s_and_b64 s[8:9], s[8:9], exec
	s_cselect_b32 s12, 0, s16
	s_lshl_b32 s17, s12, 14
	s_add_i32 s8, s17, 0x4000
	s_cmp_lg_u32 s12, 2
	v_mul_f32_e32 v180, 0xbdd53b94, v191
	s_cselect_b32 s16, s8, 0
	v_fmamk_f32 v221, v66, 0x3dd53b94, v180
	v_fmamk_f32 v219, v64, 0x3dd53b94, v180
	v_fmamk_f32 v220, v65, 0x3dd53b94, v180
	s_lshl_b32 vcc_lo, s69, 4
	s_add_i32 vcc_lo, vcc_lo, s16
	s_mov_b32 m0, vcc_lo
	s_add_i32 vcc_hi, vcc_lo, 0x2000
	global_load_lds_dwordx4 v169, s[100:101]
	s_mov_b32 m0, vcc_hi
	s_add_i32 s8, s15, 0
	v_fmamk_f32 v218, v68, 0x3dd53b94, v180
	global_load_lds_dwordx4 v170, s[100:101]
	s_add_u32 s100, s100, 0x4000
	s_addc_u32 s101, s101, 0
	v_add_u32_e32 v68, s8, v193
	v_fmamk_f32 v217, v67, 0x3dd53b94, v180
	v_fmamk_f32 v181, v69, 0x3dd53b94, v180
	v_fmamk_f32 v182, v70, 0x3dd53b94, v180
	v_fmamk_f32 v183, v71, 0x3dd53b94, v180
	ds_read_b128 v[64:67], v68 offset:49152
	ds_read_b128 v[68:71], v68 offset:61440
	v_add_u32_e32 v162, s8, v193
	v_add_u32_e32 v253, s8, v199
	v_add_u32_e32 v252, s8, v200
	v_add_u32_e32 v244, s8, v202
	ds_read_b128 v[176:179], v253 offset:49152
	ds_read_b128 v[222:225], v253 offset:61440
	v_fmamk_f32 v80, v80, 0x3dd53b94, v180
	v_fmamk_f32 v81, v81, 0x3dd53b94, v180
	v_fmamk_f32 v82, v82, 0x3dd53b94, v180
	v_fmamk_f32 v83, v83, 0x3dd53b94, v180
	v_fmamk_f32 v84, v84, 0x3dd53b94, v180
	v_fmamk_f32 v85, v85, 0x3dd53b94, v180
	v_fmamk_f32 v86, v86, 0x3dd53b94, v180
	v_fmamk_f32 v87, v87, 0x3dd53b94, v180
	v_fmamk_f32 v88, v88, 0x3dd53b94, v180
	v_fmamk_f32 v89, v89, 0x3dd53b94, v180
	v_fmamk_f32 v90, v90, 0x3dd53b94, v180
	v_fmamk_f32 v91, v91, 0x3dd53b94, v180
	v_fmamk_f32 v92, v92, 0x3dd53b94, v180
	v_fmamk_f32 v93, v93, 0x3dd53b94, v180
	v_fmamk_f32 v94, v94, 0x3dd53b94, v180
	v_fmamk_f32 v95, v95, 0x3dd53b94, v180
	v_exp_f32_e32 v144, v80
	v_exp_f32_e32 v145, v81
	v_exp_f32_e32 v146, v82
	v_exp_f32_e32 v156, v83
	v_exp_f32_e32 v147, v84
	v_exp_f32_e32 v157, v85
	v_exp_f32_e32 v158, v86
	v_exp_f32_e32 v159, v87
	v_exp_f32_e32 v148, v88
	v_exp_f32_e32 v150, v89
	v_exp_f32_e32 v149, v90
	v_exp_f32_e32 v151, v91
	v_exp_f32_e32 v152, v92
	v_exp_f32_e32 v153, v93
	v_exp_f32_e32 v154, v94
	v_exp_f32_e32 v155, v95
	s_waitcnt lgkmcnt(2)
	v_mfma_f32_32x32x16_bf16 v[80:95], v[64:67], v[140:143], 0
	ds_read_b128 v[236:239], v252 offset:49152
	ds_read_b128 v[240:243], v252 offset:61440
	v_fmamk_f32 v184, v72, 0x3dd53b94, v180
	v_fmamk_f32 v185, v73, 0x3dd53b94, v180
	v_fmamk_f32 v212, v74, 0x3dd53b94, v180
	v_fmamk_f32 v213, v75, 0x3dd53b94, v180
	v_fmamk_f32 v214, v76, 0x3dd53b94, v180
	v_fmamk_f32 v215, v77, 0x3dd53b94, v180
	v_fmamk_f32 v216, v78, 0x3dd53b94, v180
	v_fmac_f32_e32 v180, 0x3dd53b94, v79
	v_mfma_f32_32x32x16_bf16 v[64:79], v[68:71], v[140:143], 0
	v_exp_f32_e32 v163, v220
	v_exp_f32_e32 v206, v218
	v_exp_f32_e32 v181, v181
	v_exp_f32_e32 v182, v182
	v_exp_f32_e32 v183, v183
	s_waitcnt lgkmcnt(2)
	v_mfma_f32_32x32x16_bf16 v[80:95], v[176:179], v[136:139], v[80:95]
	v_exp_f32_e32 v184, v184
	v_exp_f32_e32 v185, v185
	v_exp_f32_e32 v212, v212
	v_exp_f32_e32 v213, v213
	v_exp_f32_e32 v214, v214
	v_exp_f32_e32 v215, v215
	v_exp_f32_e32 v216, v216
	v_mfma_f32_32x32x16_bf16 v[64:79], v[222:225], v[136:139], v[64:79]
	ds_read_b128 v[176:179], v244 offset:49152
	ds_read_b128 v[222:225], v244 offset:61440
	v_exp_f32_e32 v180, v180
	s_waitcnt lgkmcnt(2)
	v_mfma_f32_32x32x16_bf16 v[80:95], v[236:239], v[132:135], v[80:95]
	v_mfma_f32_32x32x16_bf16 v[64:79], v[240:243], v[132:135], v[64:79]
	ds_read_b128 v[236:239], v162 offset:49280
	ds_read_b128 v[240:243], v162 offset:61568
	s_waitcnt lgkmcnt(2)
	v_mfma_f32_32x32x16_bf16 v[80:95], v[176:179], v[128:131], v[80:95]
	v_mfma_f32_32x32x16_bf16 v[64:79], v[222:225], v[128:131], v[64:79]
	ds_read_b128 v[176:179], v253 offset:49280
	ds_read_b128 v[222:225], v253 offset:61568
	s_waitcnt lgkmcnt(2)
	v_mfma_f32_32x32x16_bf16 v[80:95], v[236:239], v[124:127], v[80:95]
	v_mfma_f32_32x32x16_bf16 v[64:79], v[240:243], v[124:127], v[64:79]
	ds_read_b128 v[236:239], v252 offset:49280
	ds_read_b128 v[240:243], v252 offset:61568
	s_waitcnt lgkmcnt(2)
	v_mfma_f32_32x32x16_bf16 v[80:95], v[176:179], v[120:123], v[80:95]
	v_mfma_f32_32x32x16_bf16 v[64:79], v[222:225], v[120:123], v[64:79]
	ds_read_b128 v[176:179], v244 offset:49280
	ds_read_b128 v[222:225], v244 offset:61568
	s_waitcnt lgkmcnt(2)
	v_mfma_f32_32x32x16_bf16 v[80:95], v[236:239], v[116:119], v[80:95]
	v_mfma_f32_32x32x16_bf16 v[64:79], v[240:243], v[116:119], v[64:79]
	ds_read_b128 v[236:239], v162 offset:49408
	ds_read_b128 v[240:243], v162 offset:61696
	s_waitcnt lgkmcnt(2)
	v_mfma_f32_32x32x16_bf16 v[80:95], v[176:179], v[112:115], v[80:95]
	v_mfma_f32_32x32x16_bf16 v[64:79], v[222:225], v[112:115], v[64:79]
	ds_read_b128 v[176:179], v253 offset:49408
	ds_read_b128 v[222:225], v253 offset:61696
	s_waitcnt lgkmcnt(2)
	v_mfma_f32_32x32x16_bf16 v[80:95], v[236:239], v[108:111], v[80:95]
	v_mfma_f32_32x32x16_bf16 v[64:79], v[240:243], v[108:111], v[64:79]
	ds_read_b128 v[236:239], v252 offset:49408
	ds_read_b128 v[240:243], v252 offset:61696
	s_waitcnt lgkmcnt(2)
	v_mfma_f32_32x32x16_bf16 v[80:95], v[176:179], v[104:107], v[80:95]
	v_mfma_f32_32x32x16_bf16 v[64:79], v[222:225], v[104:107], v[64:79]
	ds_read_b128 v[176:179], v244 offset:49408
	ds_read_b128 v[222:225], v244 offset:61696
	v_add_u32_e32 v252, s14, v190
	ds_read_b64_tr_b16 v[244:245], v252
	ds_read_b64_tr_b16 v[246:247], v252 offset:2048
	ds_read_b64_tr_b16 v[248:249], v252 offset:4096
	ds_read_b64_tr_b16 v[250:251], v252 offset:6144
	v_exp_f32_e32 v162, v219
	s_waitcnt lgkmcnt(6)
; __device__ __forceinline__ void partialSM(f32x16& p0, f32x16& p1, float& m_reg, float& mn, float& alpha) {
;   constexpr float C = ASCALE * 1.4426950408889634f;
;   float pmax = p0[0]; for (int r = 1; r < 16; ++r) pmax = fmaxf(pmax, p0[r]); for (int r = 0; r < 16; ++r) pmax = fmaxf(pmax, p1[r]);
;   { auto rr = __builtin_amdgcn_permlane32_swap(__float_as_uint(pmax), __float_as_uint(pmax), false, false);
;     pmax = fmaxf(__uint_as_float(rr[0]), __uint_as_float(rr[1])); }
;   if (__builtin_expect(__all(pmax - m_reg <= THR / ASCALE), 1)) { mn = m_reg; alpha = 1.f; }
;   else { mn = fmaxf(m_reg, pmax); alpha = __builtin_amdgcn_exp2f((m_reg - mn) * C); m_reg = mn; }
;   float mnC = -mn * C;
;   for (int r = 0; r < 16; ++r) p0[r] = fmaf(p0[r], C, mnC); for (int r = 0; r < 16; ++r) p1[r] = fmaf(p1[r], C, mnC);
;   for (int r = 0; r < 16; ++r) p0[r] = __builtin_amdgcn_exp2f(p0[r]);
; }
; __device__ __forceinline__ void finishSM(f32x16& p0, f32x16& p1, float alpha, float& l_reg, bf16x8& pa0, bf16x8& pa1, bf16x8& pa2, bf16x8& pa3) {
;   for (int r = 0; r < 16; ++r) p1[r] = __builtin_amdgcn_exp2f(p1[r]);
;   float ps = 0; for (int r = 0; r < 16; ++r) ps += p0[r]; for (int r = 0; r < 16; ++r) ps += p1[r];
;   { auto rr = __builtin_amdgcn_permlane32_swap(__float_as_uint(ps), __float_as_uint(ps), false, false);
;     ps = __uint_as_float(rr[0]) + __uint_as_float(rr[1]); }
;   l_reg = l_reg * alpha + ps;
;     ...
;   PK4(p0, 0, pa0); PK4(p0, 8, pa1); PK4(p1, 0, pa2); PK4(p1, 8, pa3);
;     ...
; }
; __device__ __forceinline__ void qkt(f32x16& p0, f32x16& p1, const char* Ks, const bf16x8* qr, int r32, int hi) {
;   p0 = f32x16{}; p1 = f32x16{};
; #pragma unroll
;   for (int d0 = 0; d0 < 12; ++d0) { int cb = (d0 * 16 + hi * 8) * 2;
;     bf16x8 b0 = *reinterpret_cast<const bf16x8*>(Ks + KSWZ(r32, cb));
;     bf16x8 b1 = *reinterpret_cast<const bf16x8*>(Ks + KSWZ(32 + r32, cb));
;     p0 = __builtin_amdgcn_mfma_f32_32x32x16_bf16(b0, qr[d0], p0, 0, 0, 0);
;     p1 = __builtin_amdgcn_mfma_f32_32x32x16_bf16(b1, qr[d0], p1, 0, 0, 0); }
; }
; __device__ __forceinline__ int v_st(int k, int c) { const int kk = (k & ~0xC) | ((k & 4) << 1) | ((k & 8) >> 1); return ((kk >> 3) * 4 + (c >> 5)) * 512 + ((kk & 7) * 32 + (c & 31)) * 2; }
; __device__ __forceinline__ int v_rd_base(int lane) { return ((lane & 3) << 3) | (((lane >> 2) & 3) << 6) | (((lane >> 4) & 1) << 5) | (((lane >> 5) & 1) << 8); }
	v_mfma_f32_32x32x16_bf16 v[80:95], v[236:239], v[100:103], v[80:95]
	v_mfma_f32_32x32x16_bf16 v[64:79], v[240:243], v[100:103], v[64:79]
	s_waitcnt lgkmcnt(4)
	v_mfma_f32_32x32x16_bf16 v[80:95], v[176:179], v[96:99], v[80:95]
	v_add_f32_e32 v177, v144, v145
	v_add_f32_e32 v177, v146, v177
	v_add_f32_e32 v177, v156, v177
	v_add_f32_e32 v177, v147, v177
	v_add_f32_e32 v177, v157, v177
	v_add_f32_e32 v177, v158, v177
	v_add_f32_e32 v177, v159, v177
	v_add_f32_e32 v177, v148, v177
	v_add_f32_e32 v177, v150, v177
	v_add_f32_e32 v177, v149, v177
	v_add_f32_e32 v177, v151, v177
	v_add_f32_e32 v177, v152, v177
	v_add_f32_e32 v177, v153, v177
	v_exp_f32_e32 v176, v221
	v_add_f32_e32 v177, v154, v177
	v_exp_f32_e32 v179, v217
	v_add_f32_e32 v177, v155, v177
	v_add_f32_e32 v177, v162, v177
	v_add_f32_e32 v177, v163, v177
	v_add_f32_e32 v177, v176, v177
	v_add_f32_e32 v177, v179, v177
	v_add_f32_e32 v177, v206, v177
	v_add_f32_e32 v177, v181, v177
	v_add_f32_e32 v177, v182, v177
	v_add_f32_e32 v177, v183, v177
	v_add_f32_e32 v177, v184, v177
	v_add_f32_e32 v177, v185, v177
	v_cvt_pk_bf16_f32 v144, v144, v145
	v_cvt_pk_bf16_f32 v145, v146, v156
	v_cvt_pk_bf16_f32 v146, v147, v157
	v_cvt_pk_bf16_f32 v147, v158, v159
	v_add_f32_e32 v177, v212, v177
	v_add_f32_e32 v177, v213, v177
	v_add_f32_e32 v177, v214, v177
	v_add_f32_e32 v177, v215, v177
	v_add_f32_e32 v177, v216, v177
	v_cvt_pk_bf16_f32 v148, v148, v150
	v_cvt_pk_bf16_f32 v150, v152, v153
	v_cvt_pk_bf16_f32 v152, v162, v163
	v_mfma_f32_32x32x16_bf16 v[64:79], v[222:225], v[96:99], v[64:79]
	v_add_f32_e32 v177, v180, v177
	v_cvt_pk_bf16_f32 v149, v149, v151
	v_cvt_pk_bf16_f32 v151, v154, v155
	v_cvt_pk_bf16_f32 v154, v206, v181
	v_cvt_pk_bf16_f32 v155, v182, v183
	v_cvt_pk_bf16_f32 v157, v212, v213
	v_cvt_pk_bf16_f32 v158, v214, v215
	v_cvt_pk_bf16_f32 v159, v216, v180
	ds_read_b64_tr_b16 v[216:217], v252 offset:8192
	ds_read_b64_tr_b16 v[218:219], v252 offset:10240
	ds_read_b64_tr_b16 v[220:221], v252 offset:12288
	ds_read_b64_tr_b16 v[222:223], v252 offset:14336
	s_waitcnt lgkmcnt(4)
	v_mfma_f32_32x32x16_bf16 v[0:15], v[144:147], v[244:247], v[0:15]
	ds_read_b64_tr_b16 v[180:181], v252 offset:512
	ds_read_b64_tr_b16 v[182:183], v252 offset:2560
	v_cvt_pk_bf16_f32 v153, v176, v179
	v_mfma_f32_32x32x16_bf16 v[0:15], v[148:151], v[248:251], v[0:15]
	ds_read_b64_tr_b16 v[212:213], v252 offset:4608
	ds_read_b64_tr_b16 v[214:215], v252 offset:6656
	v_cvt_pk_bf16_f32 v156, v184, v185
	s_waitcnt lgkmcnt(6)
	v_mfma_f32_32x32x16_bf16 v[0:15], v[152:155], v[216:219], v[0:15]
	ds_read_b64_tr_b16 v[216:217], v252 offset:8704
	ds_read_b64_tr_b16 v[218:219], v252 offset:10752
	v_mov_b32_e32 v178, v177
	s_nop 1
	v_permlane32_swap_b32_e32 v177, v178
	s_waitcnt lgkmcnt(6)
	v_mfma_f32_32x32x16_bf16 v[0:15], v[156:159], v[220:223], v[0:15]
	ds_read_b64_tr_b16 v[220:221], v252 offset:12800
	ds_read_b64_tr_b16 v[222:223], v252 offset:14848
	s_waitcnt lgkmcnt(6)
	v_mfma_f32_32x32x16_bf16 v[48:63], v[144:147], v[180:183], v[48:63]
	ds_read_b64_tr_b16 v[180:181], v252 offset:1024
	ds_read_b64_tr_b16 v[182:183], v252 offset:3072
	s_waitcnt lgkmcnt(6)
	v_mfma_f32_32x32x16_bf16 v[48:63], v[148:151], v[212:215], v[48:63]
	ds_read_b64_tr_b16 v[212:213], v252 offset:5120
	ds_read_b64_tr_b16 v[214:215], v252 offset:7168
	s_waitcnt lgkmcnt(6)
	v_mfma_f32_32x32x16_bf16 v[48:63], v[152:155], v[216:219], v[48:63]
	ds_read_b64_tr_b16 v[216:217], v252 offset:9216
	ds_read_b64_tr_b16 v[218:219], v252 offset:11264
	s_waitcnt lgkmcnt(6)
	v_mfma_f32_32x32x16_bf16 v[48:63], v[156:159], v[220:223], v[48:63]
	ds_read_b64_tr_b16 v[220:221], v252 offset:13312
	ds_read_b64_tr_b16 v[222:223], v252 offset:15360
	s_waitcnt lgkmcnt(6)
	v_mfma_f32_32x32x16_bf16 v[32:47], v[144:147], v[180:183], v[32:47]
	ds_read_b64_tr_b16 v[180:181], v252 offset:1536
	ds_read_b64_tr_b16 v[182:183], v252 offset:3584
	s_waitcnt lgkmcnt(6)
	v_mfma_f32_32x32x16_bf16 v[32:47], v[148:151], v[212:215], v[32:47]
	ds_read_b64_tr_b16 v[212:213], v252 offset:5632
	ds_read_b64_tr_b16 v[214:215], v252 offset:7680
	s_waitcnt lgkmcnt(6)
	v_mfma_f32_32x32x16_bf16 v[32:47], v[152:155], v[216:219], v[32:47]
	ds_read_b64_tr_b16 v[216:217], v252 offset:9728
	ds_read_b64_tr_b16 v[218:219], v252 offset:11776
	s_waitcnt lgkmcnt(6)
	v_mfma_f32_32x32x16_bf16 v[32:47], v[156:159], v[220:223], v[32:47]
	ds_read_b64_tr_b16 v[220:221], v252 offset:13824
	ds_read_b64_tr_b16 v[222:223], v252 offset:15872
	s_waitcnt lgkmcnt(6)
	v_mfma_f32_32x32x16_bf16 v[16:31], v[144:147], v[180:183], v[16:31]
	v_max_f32_e32 v144, v80, v81
	v_max3_f32 v144, v144, v82, v83
	v_max3_f32 v144, v144, v84, v85
	v_max3_f32 v144, v144, v86, v87
	v_max3_f32 v144, v144, v88, v89
	v_max3_f32 v144, v144, v90, v91
	v_max3_f32 v144, v144, v92, v93
	s_waitcnt lgkmcnt(4)
	v_mfma_f32_32x32x16_bf16 v[16:31], v[148:151], v[212:215], v[16:31]
	v_max3_f32 v144, v144, v94, v95
	v_max3_f32 v144, v144, v64, v65
	v_max3_f32 v144, v144, v66, v67
	v_max3_f32 v144, v144, v68, v69
	v_max3_f32 v144, v144, v70, v71
	v_max3_f32 v144, v144, v72, v73
	v_max3_f32 v144, v144, v74, v75
	v_max3_f32 v144, v144, v76, v77
	s_waitcnt lgkmcnt(2)
	v_mfma_f32_32x32x16_bf16 v[16:31], v[152:155], v[216:219], v[16:31]
	v_max3_f32 v144, v144, v78, v79
	v_mov_b32_e32 v145, v144
	s_nop 1
	v_permlane32_swap_b32_e32 v144, v145
	v_max_f32_e32 v144, v144, v145
	v_sub_f32_e32 v145, v144, v191
	v_cmp_ge_f32_e32 vcc, s35, v145
	v_max_f32_e32 v144, v191, v144
	s_waitcnt lgkmcnt(0)
	v_mfma_f32_32x32x16_bf16 v[16:31], v[156:159], v[220:223], v[16:31]
	v_sub_f32_e32 v145, v191, v144
	v_mul_f32_e32 v145, 0x3dd53b94, v145
	v_exp_f32_e32 v145, v145
	s_cmp_eq_u64 vcc, exec
	s_cselect_b64 s[8:9], -1, 0
	v_cndmask_b32_e64 v176, v145, 1.0, s[8:9]
	v_cmp_gt_f32_e32 vcc, 1.0, v176
	s_cbranch_vccz .LBB0_342
	s_and_saveexec_b64 s[14:15], s[6:7]
	ds_write_b32 v188, v176 offset:128
	s_or_b64 exec, exec, s[14:15]
	s_waitcnt lgkmcnt(0)
	v_add_u32_e32 v145, v165, v160
	ds_read_b128 v[146:149], v145 offset:224
	ds_read_b128 v[150:153], v145 offset:192
	ds_read_b128 v[154:157], v145 offset:160
	ds_read_b128 v[180:183], v145 offset:128
	s_waitcnt lgkmcnt(0)
	v_pk_mul_f32 v[12:13], v[12:13], v[146:147]
	v_pk_mul_f32 v[8:9], v[8:9], v[150:151]
	v_pk_mul_f32 v[4:5], v[4:5], v[154:155]
	v_pk_mul_f32 v[14:15], v[14:15], v[148:149]
	v_pk_mul_f32 v[10:11], v[10:11], v[152:153]
	v_pk_mul_f32 v[6:7], v[6:7], v[156:157]
	v_pk_mul_f32 v[2:3], v[2:3], v[182:183]
	v_pk_mul_f32 v[0:1], v[0:1], v[180:181]
	v_pk_mul_f32 v[60:61], v[60:61], v[146:147]
	v_pk_mul_f32 v[56:57], v[56:57], v[150:151]
	v_pk_mul_f32 v[52:53], v[52:53], v[154:155]
	v_pk_mul_f32 v[62:63], v[62:63], v[148:149]
	v_pk_mul_f32 v[58:59], v[58:59], v[152:153]
	v_pk_mul_f32 v[54:55], v[54:55], v[156:157]
	v_pk_mul_f32 v[50:51], v[50:51], v[182:183]
	v_pk_mul_f32 v[48:49], v[48:49], v[180:181]
	v_pk_mul_f32 v[44:45], v[44:45], v[146:147]
	v_pk_mul_f32 v[40:41], v[40:41], v[150:151]
	v_pk_mul_f32 v[36:37], v[36:37], v[154:155]
	v_pk_mul_f32 v[46:47], v[46:47], v[148:149]
	v_pk_mul_f32 v[42:43], v[42:43], v[152:153]
	v_pk_mul_f32 v[38:39], v[38:39], v[156:157]
	v_pk_mul_f32 v[34:35], v[34:35], v[182:183]
	v_pk_mul_f32 v[32:33], v[32:33], v[180:181]
	v_pk_mul_f32 v[28:29], v[28:29], v[146:147]
	v_pk_mul_f32 v[24:25], v[24:25], v[150:151]
	v_pk_mul_f32 v[20:21], v[20:21], v[154:155]
	v_pk_mul_f32 v[30:31], v[30:31], v[148:149]
	v_pk_mul_f32 v[26:27], v[26:27], v[152:153]
	v_pk_mul_f32 v[22:23], v[22:23], v[156:157]
	v_pk_mul_f32 v[18:19], v[18:19], v[182:183]
	v_pk_mul_f32 v[16:17], v[16:17], v[180:181]

; #define SBAR() __builtin_amdgcn_sched_barrier(0)
; #define TBAR(n) do { asm volatile("s_waitcnt vmcnt(" #n ") lgkmcnt(0)" ::: "memory"); __builtin_amdgcn_s_barrier(); SBAR(); } while (0)
; __device__ __forceinline__ void partialSM(f32x16& p0, f32x16& p1, float& m_reg, float& mn, float& alpha) {
;     ...
;   else { mn = fmaxf(m_reg, pmax); alpha = __builtin_amdgcn_exp2f((m_reg - mn) * C); m_reg = mn; }
;   float mnC = -mn * C;
;   for (int r = 0; r < 16; ++r) p0[r] = fmaf(p0[r], C, mnC); for (int r = 0; r < 16; ++r) p1[r] = fmaf(p1[r], C, mnC);
;   for (int r = 0; r < 16; ++r) p0[r] = __builtin_amdgcn_exp2f(p0[r]);
; }
; __device__ __forceinline__ void finishSM(f32x16& p0, f32x16& p1, float alpha, float& l_reg, bf16x8& pa0, bf16x8& pa1, bf16x8& pa2, bf16x8& pa3) {
;   for (int r = 0; r < 16; ++r) p1[r] = __builtin_amdgcn_exp2f(p1[r]);
;   float ps = 0; for (int r = 0; r < 16; ++r) ps += p0[r]; for (int r = 0; r < 16; ++r) ps += p1[r];
;   { auto rr = __builtin_amdgcn_permlane32_swap(__float_as_uint(ps), __float_as_uint(ps), false, false);
;     ps = __uint_as_float(rr[0]) + __uint_as_float(rr[1]); }
;   l_reg = l_reg * alpha + ps;
;     ...
;   PK4(p0, 0, pa0); PK4(p0, 8, pa1); PK4(p1, 0, pa2); PK4(p1, 8, pa3);
; __device__ __forceinline__ void attn_body(const u16* __restrict__ Qb, const u16* __restrict__ Kh, const u16* __restrict__ Vh,
;                                           u16* __restrict__ Ob, int seq, int wvs) {
;     ...
;   TBAR(0);
;   finishSM(pB0, pB1, alB, l_reg, pa0, pa1, pa2, pa3); SBAR();
;   pv_d0(o, vb0 + sV * SHM_V, pa0, pa1, pa2, pa3);
.LBB0_376:
	v_cndmask_b32_e64 v97, v97, v191, s[8:9]
	s_waitcnt vmcnt(0) lgkmcnt(0)
	v_mul_f32_e32 v97, 0xbdd53b94, v97
	v_fmamk_f32 v80, v80, 0x3dd53b94, v97
	v_fmamk_f32 v81, v81, 0x3dd53b94, v97
	v_fmamk_f32 v82, v82, 0x3dd53b94, v97
	v_fmamk_f32 v83, v83, 0x3dd53b94, v97
	v_fmamk_f32 v84, v84, 0x3dd53b94, v97
	v_fmamk_f32 v85, v85, 0x3dd53b94, v97
	v_fmamk_f32 v86, v86, 0x3dd53b94, v97
	v_fmamk_f32 v87, v87, 0x3dd53b94, v97
	v_fmamk_f32 v88, v88, 0x3dd53b94, v97
	v_fmamk_f32 v89, v89, 0x3dd53b94, v97
	v_fmamk_f32 v90, v90, 0x3dd53b94, v97
	v_fmamk_f32 v91, v91, 0x3dd53b94, v97
	v_fmamk_f32 v92, v92, 0x3dd53b94, v97
	v_fmamk_f32 v93, v93, 0x3dd53b94, v97
	v_fmamk_f32 v94, v94, 0x3dd53b94, v97
	v_fmamk_f32 v95, v95, 0x3dd53b94, v97
	v_fmamk_f32 v64, v64, 0x3dd53b94, v97
	v_fmamk_f32 v65, v65, 0x3dd53b94, v97
	v_fmamk_f32 v66, v66, 0x3dd53b94, v97
	v_fmamk_f32 v67, v67, 0x3dd53b94, v97
	v_fmamk_f32 v68, v68, 0x3dd53b94, v97
	v_fmamk_f32 v69, v69, 0x3dd53b94, v97
	v_fmamk_f32 v70, v70, 0x3dd53b94, v97
	v_fmamk_f32 v71, v71, 0x3dd53b94, v97
	v_fmamk_f32 v72, v72, 0x3dd53b94, v97
	v_fmamk_f32 v73, v73, 0x3dd53b94, v97
	v_fmamk_f32 v74, v74, 0x3dd53b94, v97
	v_fmamk_f32 v75, v75, 0x3dd53b94, v97
	v_fmamk_f32 v76, v76, 0x3dd53b94, v97
	v_fmamk_f32 v77, v77, 0x3dd53b94, v97
	v_fmamk_f32 v78, v78, 0x3dd53b94, v97
	v_fmac_f32_e32 v97, 0x3dd53b94, v79
	v_exp_f32_e32 v79, v80
	v_exp_f32_e32 v98, v81
	v_exp_f32_e32 v82, v82
	v_exp_f32_e32 v83, v83
	v_exp_f32_e32 v84, v84
	v_exp_f32_e32 v85, v85
	v_exp_f32_e32 v86, v86
	v_exp_f32_e32 v87, v87
	v_exp_f32_e32 v88, v88
	v_exp_f32_e32 v89, v89
	v_exp_f32_e32 v90, v90
	v_exp_f32_e32 v91, v91
	v_exp_f32_e32 v92, v92
	v_exp_f32_e32 v93, v93
	v_exp_f32_e32 v94, v94
	v_exp_f32_e32 v95, v95
	s_barrier
	v_exp_f32_e32 v99, v68
	v_add_f32_e32 v68, 0, v79
	v_add_f32_e32 v68, v98, v68
	v_add_f32_e32 v68, v82, v68
	v_add_f32_e32 v68, v83, v68
	v_add_f32_e32 v68, v84, v68
	v_add_f32_e32 v68, v85, v68
	v_add_f32_e32 v68, v86, v68
	v_add_f32_e32 v68, v87, v68
	v_add_f32_e32 v68, v88, v68
	v_add_f32_e32 v68, v89, v68
	v_add_f32_e32 v68, v90, v68
	v_add_f32_e32 v68, v91, v68
	v_exp_f32_e32 v64, v64
	v_add_f32_e32 v68, v92, v68
	v_exp_f32_e32 v65, v65
	v_add_f32_e32 v68, v93, v68
	v_exp_f32_e32 v66, v66
	v_add_f32_e32 v68, v94, v68
	v_exp_f32_e32 v67, v67
	v_add_f32_e32 v68, v95, v68
	v_add_f32_e32 v68, v64, v68
	v_exp_f32_e32 v100, v69
	v_add_f32_e32 v68, v65, v68
	v_exp_f32_e32 v101, v70
	v_add_f32_e32 v68, v66, v68
	v_exp_f32_e32 v71, v71
	v_add_f32_e32 v68, v67, v68
	v_exp_f32_e32 v102, v72
	v_add_f32_e32 v68, v99, v68
	v_exp_f32_e32 v103, v73
	v_add_f32_e32 v68, v100, v68
	v_exp_f32_e32 v104, v74
	v_add_f32_e32 v68, v101, v68
	v_exp_f32_e32 v105, v75
	v_add_f32_e32 v68, v71, v68
	v_exp_f32_e32 v106, v76
	v_add_f32_e32 v68, v102, v68
	v_exp_f32_e32 v107, v77
	v_add_f32_e32 v68, v103, v68
	v_exp_f32_e32 v108, v78
	v_add_f32_e32 v68, v104, v68
	v_exp_f32_e32 v97, v97
	v_add_f32_e32 v68, v105, v68
	v_add_f32_e32 v68, v106, v68
	v_add_f32_e32 v68, v107, v68
	v_add_f32_e32 v68, v108, v68
	v_add_f32_e32 v80, v97, v68
	v_mov_b32_e32 v81, v80
	s_nop 1
	v_permlane32_swap_b32_e32 v80, v81
	v_cvt_pk_bf16_f32 v76, v79, v98
	v_cvt_pk_bf16_f32 v77, v82, v83
	v_cvt_pk_bf16_f32 v78, v84, v85
	v_cvt_pk_bf16_f32 v79, v86, v87
	v_cvt_pk_bf16_f32 v72, v88, v89
	v_cvt_pk_bf16_f32 v73, v90, v91
	v_cvt_pk_bf16_f32 v74, v92, v93
	v_cvt_pk_bf16_f32 v75, v94, v95
	v_cvt_pk_bf16_f32 v68, v64, v65
	v_cvt_pk_bf16_f32 v69, v66, v67
	v_cvt_pk_bf16_f32 v70, v99, v100
	v_cvt_pk_bf16_f32 v71, v101, v71
	v_cvt_pk_bf16_f32 v64, v102, v103
	v_cvt_pk_bf16_f32 v65, v104, v105
	v_cvt_pk_bf16_f32 v66, v106, v107
	v_cvt_pk_bf16_f32 v67, v108, v97
	v_add_u32_e32 v86, s16, v190
	ds_read_b64_tr_b16 v[82:83], v86
	ds_read_b64_tr_b16 v[84:85], v86 offset:2048
	s_waitcnt lgkmcnt(0)
	v_mfma_f32_32x32x16_bf16 v[0:15], v[76:79], v[82:85], v[0:15]
	ds_read_b64_tr_b16 v[82:83], v86 offset:4096
	ds_read_b64_tr_b16 v[84:85], v86 offset:6144
	s_waitcnt lgkmcnt(0)
	v_mfma_f32_32x32x16_bf16 v[0:15], v[72:75], v[82:85], v[0:15]
	ds_read_b64_tr_b16 v[82:83], v86 offset:8192
	ds_read_b64_tr_b16 v[84:85], v86 offset:10240
	s_waitcnt lgkmcnt(0)
	v_mfma_f32_32x32x16_bf16 v[0:15], v[68:71], v[82:85], v[0:15]
	ds_read_b64_tr_b16 v[82:83], v86 offset:12288
	ds_read_b64_tr_b16 v[84:85], v86 offset:14336
	s_waitcnt lgkmcnt(0)
	v_mfma_f32_32x32x16_bf16 v[0:15], v[64:67], v[82:85], v[0:15]
	ds_read_b64_tr_b16 v[82:83], v86 offset:512
	ds_read_b64_tr_b16 v[84:85], v86 offset:2560
	s_waitcnt lgkmcnt(0)
	v_mfma_f32_32x32x16_bf16 v[48:63], v[76:79], v[82:85], v[48:63]
	ds_read_b64_tr_b16 v[82:83], v86 offset:4608
	ds_read_b64_tr_b16 v[84:85], v86 offset:6656
	s_waitcnt lgkmcnt(0)
	v_mfma_f32_32x32x16_bf16 v[48:63], v[72:75], v[82:85], v[48:63]
	ds_read_b64_tr_b16 v[82:83], v86 offset:8704
	ds_read_b64_tr_b16 v[84:85], v86 offset:10752
	s_waitcnt lgkmcnt(0)
	v_mfma_f32_32x32x16_bf16 v[48:63], v[68:71], v[82:85], v[48:63]
	ds_read_b64_tr_b16 v[82:83], v86 offset:12800
	ds_read_b64_tr_b16 v[84:85], v86 offset:14848
	s_waitcnt lgkmcnt(0)
	v_mfma_f32_32x32x16_bf16 v[48:63], v[64:67], v[82:85], v[48:63]
	ds_read_b64_tr_b16 v[82:83], v86 offset:1024
	ds_read_b64_tr_b16 v[84:85], v86 offset:3072
	s_waitcnt lgkmcnt(0)
	v_mfma_f32_32x32x16_bf16 v[32:47], v[76:79], v[82:85], v[32:47]
	ds_read_b64_tr_b16 v[82:83], v86 offset:5120
	ds_read_b64_tr_b16 v[84:85], v86 offset:7168
	s_waitcnt lgkmcnt(0)
	v_mfma_f32_32x32x16_bf16 v[32:47], v[72:75], v[82:85], v[32:47]
	ds_read_b64_tr_b16 v[82:83], v86 offset:9216
	ds_read_b64_tr_b16 v[84:85], v86 offset:11264
	s_waitcnt lgkmcnt(0)
; __device__ __forceinline__ u16 f2bf(float x) { return (u16)(cvtpk(x, 0.f) & 0xffffu); }
; __device__ __forceinline__ int crow(int r, int hi) { return (r & 3) + 8 * (r >> 2) + 4 * hi; }
; __device__ __forceinline__ void attn_body(const u16* __restrict__ Qb, const u16* __restrict__ Kh, const u16* __restrict__ Vh,
;                                           u16* __restrict__ Ob, int seq, int wvs) {
;     ...
;   if (hi == 0) li_l[r32] = l_reg; asm volatile("s_waitcnt lgkmcnt(0)" ::: "memory");
;   float rli[16];
; #pragma unroll
;   for (int r = 0; r < 16; ++r) rli[r] = __builtin_amdgcn_rcpf(li_l[crow(r, hi)]);
;   u16* Ow = Ob + (long)(wid * QBLK) * DM;
; #pragma unroll
;   for (int r = 0; r < 16; ++r) { int orow = crow(r, hi);
; #pragma unroll
;     for (int d0 = 0; d0 < 4; ++d0) Ow[(long)orow * DM + d0 * 32 + r32] = f2bf(o[d0][r] * rli[r]); }
	v_mfma_f32_32x32x16_bf16 v[32:47], v[68:71], v[82:85], v[32:47]
	ds_read_b64_tr_b16 v[82:83], v86 offset:13312
	ds_read_b64_tr_b16 v[84:85], v86 offset:15360
	s_waitcnt lgkmcnt(0)
	v_mfma_f32_32x32x16_bf16 v[32:47], v[64:67], v[82:85], v[32:47]
	ds_read_b64_tr_b16 v[82:83], v86 offset:1536
	ds_read_b64_tr_b16 v[84:85], v86 offset:3584
	s_waitcnt lgkmcnt(0)
	v_mfma_f32_32x32x16_bf16 v[16:31], v[76:79], v[82:85], v[16:31]
	ds_read_b64_tr_b16 v[76:77], v86 offset:5632
	ds_read_b64_tr_b16 v[78:79], v86 offset:7680
	s_waitcnt lgkmcnt(0)
	v_mfma_f32_32x32x16_bf16 v[16:31], v[72:75], v[76:79], v[16:31]
	ds_read_b64_tr_b16 v[72:73], v86 offset:9728
	ds_read_b64_tr_b16 v[74:75], v86 offset:11776
	s_waitcnt lgkmcnt(0)
	v_mfma_f32_32x32x16_bf16 v[16:31], v[68:71], v[72:75], v[16:31]
	ds_read_b64_tr_b16 v[68:69], v86 offset:13824
	ds_read_b64_tr_b16 v[70:71], v86 offset:15872
	s_waitcnt lgkmcnt(0)
	v_mfma_f32_32x32x16_bf16 v[16:31], v[64:67], v[68:71], v[16:31]
	s_and_saveexec_b64 s[4:5], s[6:7]
	v_add_f32_e32 v64, v112, v113
	v_fmac_f32_e32 v64, v189, v176
	v_add_f32_e32 v65, v80, v81
	v_fmac_f32_e32 v65, v64, v96
	ds_write_b32 v188, v65
	s_or_b64 exec, exec, s[4:5]
	s_waitcnt lgkmcnt(0)
	v_add_u32_e32 v72, v165, v160
	ds_read_b128 v[64:67], v72
	ds_read_b128 v[68:71], v72 offset:32
	v_ashrrev_i32_e32 v165, 31, v164
	v_readlane_b32 s4, v254, 43
	v_readlane_b32 s5, v254, 44
	s_waitcnt lgkmcnt(0)
	v_rcp_f32_e32 v73, v64
	v_rcp_f32_e32 v74, v65
	v_rcp_f32_e32 v75, v66
	v_rcp_f32_e32 v76, v67
	ds_read_b128 v[64:67], v72 offset:64
	v_rcp_f32_e32 v77, v68
	v_rcp_f32_e32 v78, v69
	v_rcp_f32_e32 v79, v70
	v_rcp_f32_e32 v80, v71
	ds_read_b128 v[68:71], v72 offset:96
	s_waitcnt lgkmcnt(0)
	v_rcp_f32_e32 v72, v64
	v_rcp_f32_e32 v81, v65
	v_lshlrev_b64 v[64:65], 12, v[164:165]
	v_lshl_add_u64 v[64:65], s[4:5], 0, v[64:65]
	v_lshlrev_b32_e32 v160, 1, v187
	v_rcp_f32_e32 v82, v66
	v_rcp_f32_e32 v83, v67
	v_lshlrev_b32_e32 v66, 14, v186
	v_lshl_add_u64 v[64:65], v[64:65], 0, v[160:161]
	v_mov_b32_e32 v67, v161
	v_mul_f32_e32 v0, v0, v73
	v_lshl_add_u64 v[64:65], v[64:65], 0, v[66:67]
	v_cvt_pk_bf16_f32 v0, v0, s0
	global_store_short v[64:65], v0, off
	v_mul_f32_e32 v0, v48, v73
	v_cvt_pk_bf16_f32 v0, v0, s0
	global_store_short v[64:65], v0, off offset:64
	v_mul_f32_e32 v0, v32, v73
	v_cvt_pk_bf16_f32 v0, v0, s0
	global_store_short v[64:65], v0, off offset:128
	v_mul_f32_e32 v0, v16, v73
	v_cvt_pk_bf16_f32 v0, v0, s0
	global_store_short v[64:65], v0, off offset:192
	v_mul_f32_e32 v0, v1, v74
	s_movk_i32 s4, 0x1000
	v_cvt_pk_bf16_f32 v16, v0, s0
	v_add_co_u32_e32 v0, vcc, s4, v64
	s_movk_i32 s4, 0x2000
	s_nop 0
	v_addc_co_u32_e32 v1, vcc, 0, v65, vcc
	global_store_short v[0:1], v16, off
	v_mul_f32_e32 v16, v49, v74
	v_cvt_pk_bf16_f32 v16, v16, s0
	global_store_short v[0:1], v16, off offset:64
	v_mul_f32_e32 v16, v33, v74
	v_cvt_pk_bf16_f32 v16, v16, s0
	global_store_short v[0:1], v16, off offset:128
	v_mul_f32_e32 v16, v17, v74
	v_cvt_pk_bf16_f32 v16, v16, s0
	global_store_short v[0:1], v16, off offset:192
	v_mul_f32_e32 v0, v2, v75
	v_cvt_pk_bf16_f32 v2, v0, s0
	v_add_co_u32_e32 v0, vcc, s4, v64
	s_movk_i32 s4, 0x3000
	s_nop 0
	v_addc_co_u32_e32 v1, vcc, 0, v65, vcc
	global_store_short v[0:1], v2, off
	v_mul_f32_e32 v2, v50, v75
	v_cvt_pk_bf16_f32 v2, v2, s0
	global_store_short v[0:1], v2, off offset:64
	v_mul_f32_e32 v2, v34, v75
	v_cvt_pk_bf16_f32 v2, v2, s0
	global_store_short v[0:1], v2, off offset:128
	v_mul_f32_e32 v2, v18, v75
	v_cvt_pk_bf16_f32 v2, v2, s0
	global_store_short v[0:1], v2, off offset:192
	v_mul_f32_e32 v0, v3, v76
	v_cvt_pk_bf16_f32 v2, v0, s0
	v_add_co_u32_e32 v0, vcc, s4, v64
	s_mov_b32 s4, 0x8000
	s_nop 0
	v_addc_co_u32_e32 v1, vcc, 0, v65, vcc
	global_store_short v[0:1], v2, off
	v_mul_f32_e32 v2, v51, v76
	v_cvt_pk_bf16_f32 v2, v2, s0
	global_store_short v[0:1], v2, off offset:64
	v_mul_f32_e32 v2, v35, v76
	v_cvt_pk_bf16_f32 v2, v2, s0
	global_store_short v[0:1], v2, off offset:128
	v_mul_f32_e32 v2, v19, v76
	v_cvt_pk_bf16_f32 v2, v2, s0
	global_store_short v[0:1], v2, off offset:192
	v_mul_f32_e32 v0, v4, v77
	v_cvt_pk_bf16_f32 v2, v0, s0
	v_add_co_u32_e32 v0, vcc, s4, v64
	s_mov_b32 s4, 0x9000
	s_nop 0
	v_addc_co_u32_e32 v1, vcc, 0, v65, vcc
	global_store_short v[0:1], v2, off
	v_mul_f32_e32 v2, v52, v77
	v_cvt_pk_bf16_f32 v2, v2, s0
	global_store_short v[0:1], v2, off offset:64
	v_mul_f32_e32 v2, v36, v77
	v_cvt_pk_bf16_f32 v2, v2, s0
	global_store_short v[0:1], v2, off offset:128
	v_mul_f32_e32 v2, v20, v77
	v_cvt_pk_bf16_f32 v2, v2, s0
	global_store_short v[0:1], v2, off offset:192
	v_mul_f32_e32 v0, v5, v78
	v_cvt_pk_bf16_f32 v2, v0, s0
	v_add_co_u32_e32 v0, vcc, s4, v64
	s_mov_b32 s4, 0xa000
	s_nop 0
	v_addc_co_u32_e32 v1, vcc, 0, v65, vcc
	global_store_short v[0:1], v2, off
	v_mul_f32_e32 v2, v53, v78
	v_cvt_pk_bf16_f32 v2, v2, s0
	global_store_short v[0:1], v2, off offset:64
	v_mul_f32_e32 v2, v37, v78
	v_cvt_pk_bf16_f32 v2, v2, s0
	global_store_short v[0:1], v2, off offset:128
	v_mul_f32_e32 v2, v21, v78
	v_cvt_pk_bf16_f32 v2, v2, s0
	global_store_short v[0:1], v2, off offset:192
	v_mul_f32_e32 v0, v6, v79
	v_cvt_pk_bf16_f32 v2, v0, s0
	v_add_co_u32_e32 v0, vcc, s4, v64
	s_mov_b32 s4, 0xb000
	s_nop 0
; __device__ __forceinline__ u16 f2bf(float x) { return (u16)(cvtpk(x, 0.f) & 0xffffu); }
; __device__ __forceinline__ int crow(int r, int hi) { return (r & 3) + 8 * (r >> 2) + 4 * hi; }
; __device__ __forceinline__ void attn_body(const u16* __restrict__ Qb, const u16* __restrict__ Kh, const u16* __restrict__ Vh,
;                                           u16* __restrict__ Ob, int seq, int wvs) {
;     ...
;   for (int r = 0; r < 16; ++r) { int orow = crow(r, hi);
; #pragma unroll
;     for (int d0 = 0; d0 < 4; ++d0) Ow[(long)orow * DM + d0 * 32 + r32] = f2bf(o[d0][r] * rli[r]); }
	v_addc_co_u32_e32 v1, vcc, 0, v65, vcc
	global_store_short v[0:1], v2, off
	v_mul_f32_e32 v2, v54, v79
	v_cvt_pk_bf16_f32 v2, v2, s0
	global_store_short v[0:1], v2, off offset:64
	v_mul_f32_e32 v2, v38, v79
	v_cvt_pk_bf16_f32 v2, v2, s0
	global_store_short v[0:1], v2, off offset:128
	v_mul_f32_e32 v2, v22, v79
	v_cvt_pk_bf16_f32 v2, v2, s0
	global_store_short v[0:1], v2, off offset:192
	v_mul_f32_e32 v0, v7, v80
	v_cvt_pk_bf16_f32 v2, v0, s0
	v_add_co_u32_e32 v0, vcc, s4, v64
	s_mov_b32 s4, 0x10000
	s_nop 0
	v_addc_co_u32_e32 v1, vcc, 0, v65, vcc
	global_store_short v[0:1], v2, off
	v_mul_f32_e32 v2, v55, v80
	v_cvt_pk_bf16_f32 v2, v2, s0
	global_store_short v[0:1], v2, off offset:64
	v_mul_f32_e32 v2, v39, v80
	v_cvt_pk_bf16_f32 v2, v2, s0
	global_store_short v[0:1], v2, off offset:128
	v_mul_f32_e32 v2, v23, v80
	v_cvt_pk_bf16_f32 v2, v2, s0
	global_store_short v[0:1], v2, off offset:192
	v_mul_f32_e32 v0, v8, v72
	v_cvt_pk_bf16_f32 v2, v0, s0
	v_add_co_u32_e32 v0, vcc, s4, v64
	s_mov_b32 s4, 0x11000
	s_nop 0
	v_addc_co_u32_e32 v1, vcc, 0, v65, vcc
	global_store_short v[0:1], v2, off
	v_mul_f32_e32 v2, v56, v72
	v_cvt_pk_bf16_f32 v2, v2, s0
	global_store_short v[0:1], v2, off offset:64
	v_mul_f32_e32 v2, v40, v72
	v_cvt_pk_bf16_f32 v2, v2, s0
	global_store_short v[0:1], v2, off offset:128
	v_mul_f32_e32 v2, v24, v72
	v_cvt_pk_bf16_f32 v2, v2, s0
	global_store_short v[0:1], v2, off offset:192
	v_mul_f32_e32 v0, v9, v81
	v_cvt_pk_bf16_f32 v2, v0, s0
	v_add_co_u32_e32 v0, vcc, s4, v64
	s_mov_b32 s4, 0x12000
	s_nop 0
	v_addc_co_u32_e32 v1, vcc, 0, v65, vcc
	global_store_short v[0:1], v2, off
	v_mul_f32_e32 v2, v57, v81
	v_cvt_pk_bf16_f32 v2, v2, s0
	global_store_short v[0:1], v2, off offset:64
	v_mul_f32_e32 v2, v41, v81
	v_cvt_pk_bf16_f32 v2, v2, s0
	global_store_short v[0:1], v2, off offset:128
	v_mul_f32_e32 v2, v25, v81
	v_cvt_pk_bf16_f32 v2, v2, s0
	global_store_short v[0:1], v2, off offset:192
	v_mul_f32_e32 v0, v10, v82
	v_cvt_pk_bf16_f32 v2, v0, s0
	v_add_co_u32_e32 v0, vcc, s4, v64
	s_mov_b32 s4, 0x13000
	s_nop 0
	v_addc_co_u32_e32 v1, vcc, 0, v65, vcc
	global_store_short v[0:1], v2, off
	v_mul_f32_e32 v2, v58, v82
	v_cvt_pk_bf16_f32 v2, v2, s0
	global_store_short v[0:1], v2, off offset:64
	v_mul_f32_e32 v2, v42, v82
	v_cvt_pk_bf16_f32 v2, v2, s0
	global_store_short v[0:1], v2, off offset:128
	v_mul_f32_e32 v2, v26, v82
	v_cvt_pk_bf16_f32 v2, v2, s0
	global_store_short v[0:1], v2, off offset:192
	v_mul_f32_e32 v0, v11, v83
	v_cvt_pk_bf16_f32 v2, v0, s0
	v_add_co_u32_e32 v0, vcc, s4, v64
	v_rcp_f32_e32 v68, v68
	s_nop 0
	v_addc_co_u32_e32 v1, vcc, 0, v65, vcc
	global_store_short v[0:1], v2, off
	v_mul_f32_e32 v2, v59, v83
	v_cvt_pk_bf16_f32 v2, v2, s0
	global_store_short v[0:1], v2, off offset:64
	v_mul_f32_e32 v2, v43, v83
	v_cvt_pk_bf16_f32 v2, v2, s0
	global_store_short v[0:1], v2, off offset:128
	v_mul_f32_e32 v2, v27, v83
	v_cvt_pk_bf16_f32 v2, v2, s0
	global_store_short v[0:1], v2, off offset:192
	v_mul_f32_e32 v0, v12, v68
	s_mov_b32 s4, 0x18000
	v_cvt_pk_bf16_f32 v2, v0, s0
	v_add_co_u32_e32 v0, vcc, s4, v64
	v_rcp_f32_e32 v69, v69
	s_nop 0
	v_addc_co_u32_e32 v1, vcc, 0, v65, vcc
	global_store_short v[0:1], v2, off
	v_mul_f32_e32 v2, v60, v68
	v_cvt_pk_bf16_f32 v2, v2, s0
	global_store_short v[0:1], v2, off offset:64
	v_mul_f32_e32 v2, v44, v68
	v_cvt_pk_bf16_f32 v2, v2, s0
	global_store_short v[0:1], v2, off offset:128
	v_mul_f32_e32 v2, v28, v68
	v_cvt_pk_bf16_f32 v2, v2, s0
	global_store_short v[0:1], v2, off offset:192
	v_mul_f32_e32 v0, v13, v69
	s_mov_b32 s4, 0x19000
	v_cvt_pk_bf16_f32 v2, v0, s0
	v_add_co_u32_e32 v0, vcc, s4, v64
	v_rcp_f32_e32 v70, v70
	s_nop 0
	v_addc_co_u32_e32 v1, vcc, 0, v65, vcc
	global_store_short v[0:1], v2, off
	v_mul_f32_e32 v2, v61, v69
	v_cvt_pk_bf16_f32 v2, v2, s0
	global_store_short v[0:1], v2, off offset:64
	v_mul_f32_e32 v2, v45, v69
	v_cvt_pk_bf16_f32 v2, v2, s0
	global_store_short v[0:1], v2, off offset:128
	v_mul_f32_e32 v2, v29, v69
	v_cvt_pk_bf16_f32 v2, v2, s0
	global_store_short v[0:1], v2, off offset:192
	v_mul_f32_e32 v0, v14, v70
	s_mov_b32 s4, 0x1a000
	v_cvt_pk_bf16_f32 v2, v0, s0
	v_add_co_u32_e32 v0, vcc, s4, v64
	v_rcp_f32_e32 v71, v71
	s_nop 0
	v_addc_co_u32_e32 v1, vcc, 0, v65, vcc
	global_store_short v[0:1], v2, off
	v_mul_f32_e32 v2, v62, v70
	v_cvt_pk_bf16_f32 v2, v2, s0
	global_store_short v[0:1], v2, off offset:64
	v_mul_f32_e32 v2, v46, v70
	v_cvt_pk_bf16_f32 v2, v2, s0
	global_store_short v[0:1], v2, off offset:128
	v_mul_f32_e32 v2, v30, v70
	v_cvt_pk_bf16_f32 v2, v2, s0
	global_store_short v[0:1], v2, off offset:192
	v_mul_f32_e32 v0, v15, v71
	s_mov_b32 s4, 0x1b000
	v_cvt_pk_bf16_f32 v2, v0, s0
	v_add_co_u32_e32 v0, vcc, s4, v64
	s_add_i32 s23, s41, 1
	s_nop 0
	v_addc_co_u32_e32 v1, vcc, 0, v65, vcc
	global_store_short v[0:1], v2, off
	v_mul_f32_e32 v2, v63, v71
	v_cvt_pk_bf16_f32 v2, v2, s0
	global_store_short v[0:1], v2, off offset:64
	v_mul_f32_e32 v2, v47, v71
	v_cvt_pk_bf16_f32 v2, v2, s0
	global_store_short v[0:1], v2, off offset:128
	v_mul_f32_e32 v2, v31, v71
	v_cvt_pk_bf16_f32 v2, v2, s0
	s_mov_b64 s[24:25], 0
	global_store_short v[0:1], v2, off offset:192
	s_cmp_eq_u32 s23, s92
	s_cbranch_scc0 .LBB0_768
	s_branch .LBB0_245
